# attention tile loop instruction diet: merged lgkmcnt waits (28 -> 13 s_waitcnt per tile), M0 write / address add / LDS-DMA ordering without s_nop; GEMM loops without s_setprio toggles
# speedup vs baseline: 1.0143x; 1.0054x over previous
.Lat_ubD3:
	s_lshl_b32 s38, s36, 1
	s_add_i32 s38, s38, 2
	s_add_i32 s1, s91, 0
	s_and_b32 s1, s1, 3
	s_lshl_b32 s1, s1, 15
	s_add_i32 s1, s1, s40
	s_add_i32 m0, s1, 0x0
	v_add_u32_e32 v210, s79, v197
	global_load_lds_dwordx4 v210, s[86:87]
	s_add_i32 m0, s1, 0x400
	v_add_u32_e32 v211, s79, v198
	global_load_lds_dwordx4 v211, s[86:87]
	s_add_i32 m0, s1, 0x800
	v_add_u32_e32 v212, s79, v229
	global_load_lds_dwordx4 v212, s[86:87]
	s_add_i32 m0, s1, 0xc00
	v_add_u32_e32 v213, s79, v230
	global_load_lds_dwordx4 v213, s[86:87]
	s_add_i32 s79, s79, s41
	s_add_i32 s1, s91, 1
	s_and_b32 s1, s1, 3
	s_lshl_b32 s1, s1, 15
	s_add_i32 s1, s1, s40
	s_add_i32 m0, s1, 0x0
	v_add_u32_e32 v210, s79, v197
	global_load_lds_dwordx4 v210, s[86:87]
	s_add_i32 m0, s1, 0x400
	v_add_u32_e32 v211, s79, v198
	global_load_lds_dwordx4 v211, s[86:87]
	s_add_i32 m0, s1, 0x800
	v_add_u32_e32 v212, s79, v229
	global_load_lds_dwordx4 v212, s[86:87]
	s_add_i32 m0, s1, 0xc00
	v_add_u32_e32 v213, s79, v230
	global_load_lds_dwordx4 v213, s[86:87]
	s_add_i32 s79, s79, s41
	s_waitcnt vmcnt(0)

.Lattn_tileA:
	s_add_i32 s0, s39, 2
	s_cmp_lt_i32 s0, s38
	s_cbranch_scc0 .Lat_nodma4
	s_add_i32 s1, s91, 2
	s_and_b32 s1, s1, 3
	s_lshl_b32 s1, s1, 15
	s_add_i32 s1, s1, s40
	s_add_i32 m0, s1, 0x0
	v_add_u32_e32 v210, s79, v197
	global_load_lds_dwordx4 v210, s[86:87]
	s_add_i32 m0, s1, 0x400
	v_add_u32_e32 v211, s79, v198
	global_load_lds_dwordx4 v211, s[86:87]
	s_add_i32 m0, s1, 0x800
	v_add_u32_e32 v212, s79, v229
	global_load_lds_dwordx4 v212, s[86:87]
	s_add_i32 m0, s1, 0xc00
	v_add_u32_e32 v213, s79, v230
	global_load_lds_dwordx4 v213, s[86:87]
	s_add_i32 s79, s79, s41
.Lat_nodma4:
	s_lshl_b32 s96, s39, 6
	s_add_i32 s0, s37, 15
	s_cmp_gt_i32 s96, s0
	s_cselect_b32 vcc_hi, 1, 0
	s_cbranch_scc1 .Lat_s1end5
	ds_read_b128 v[80:83], v195
	ds_read_b128 v[84:87], v196
	ds_read_b128 v[88:91], v195 offset:4096
	ds_read_b128 v[92:95], v196 offset:4096
	ds_read_b128 v[96:99], v195 offset:8192
	ds_read_b128 v[100:103], v196 offset:8192
	ds_read_b128 v[104:107], v195 offset:12288
	ds_read_b128 v[108:111], v196 offset:12288
	s_waitcnt lgkmcnt(6)
	v_mfma_f32_16x16x32_bf16 v[144:147], v[80:83], v[64:67], v[248:251]
	ds_read_b128 v[112:115], v231
	v_mfma_f32_16x16x32_bf16 v[144:147], v[84:87], v[68:71], v[144:147]
	ds_read_b128 v[116:119], v232
	s_waitcnt lgkmcnt(6)
	v_mfma_f32_16x16x32_bf16 v[148:151], v[88:91], v[64:67], v[248:251]
	ds_read_b128 v[120:123], v231 offset:4096
	v_mfma_f32_16x16x32_bf16 v[148:151], v[92:95], v[68:71], v[148:151]
	ds_read_b128 v[124:127], v232 offset:4096
	s_waitcnt lgkmcnt(6)
	v_mfma_f32_16x16x32_bf16 v[152:155], v[96:99], v[64:67], v[248:251]
	ds_read_b128 v[128:131], v231 offset:8192
	v_mfma_f32_16x16x32_bf16 v[152:155], v[100:103], v[68:71], v[152:155]
	ds_read_b128 v[132:135], v232 offset:8192
	s_waitcnt lgkmcnt(6)
	v_mfma_f32_16x16x32_bf16 v[156:159], v[104:107], v[64:67], v[248:251]
	ds_read_b128 v[136:139], v231 offset:12288
	v_mfma_f32_16x16x32_bf16 v[156:159], v[108:111], v[68:71], v[156:159]
	ds_read_b128 v[140:143], v232 offset:12288
	s_waitcnt lgkmcnt(0)
	v_mfma_f32_16x16x32_bf16 v[160:163], v[112:115], v[72:75], v[248:251]
	v_mfma_f32_16x16x32_bf16 v[160:163], v[116:119], v[76:79], v[160:163]
	s_add_i32 s0, s96, 63
	s_cmp_gt_i32 s0, s37
	s_cselect_b32 s97, 1, 0
	s_cbranch_scc0 .Lat_nomask6
	v_subrev_u32_e32 v207, s96, v200
	v_cmp_gt_i32_e64 s[42:43], 0, v207
	v_cmp_gt_i32_e64 s[44:45], 1, v207
	v_cmp_gt_i32_e64 s[46:47], 2, v207
	v_cmp_gt_i32_e64 s[48:49], 3, v207
	v_cmp_gt_i32_e64 s[50:51], 4, v207
	v_cmp_gt_i32_e64 s[52:53], 5, v207
	v_cmp_gt_i32_e64 s[54:55], 6, v207
	v_cmp_gt_i32_e64 s[56:57], 7, v207
	v_cmp_gt_i32_e64 s[58:59], 32, v207
	v_cmp_gt_i32_e64 s[60:61], 33, v207
	v_cmp_gt_i32_e64 s[62:63], 34, v207
	v_cmp_gt_i32_e64 s[64:65], 35, v207
	v_cmp_gt_i32_e64 s[66:67], 36, v207
	v_cmp_gt_i32_e64 s[68:69], 37, v207
	v_cmp_gt_i32_e64 s[70:71], 38, v207
	v_cmp_gt_i32_e64 s[72:73], 39, v207
	v_cndmask_b32_e64 v144, v144, v201, s[42:43]
	v_cndmask_b32_e64 v145, v145, v201, s[44:45]
	v_cndmask_b32_e64 v146, v146, v201, s[46:47]
	v_cndmask_b32_e64 v147, v147, v201, s[48:49]
	v_cndmask_b32_e64 v148, v148, v201, s[50:51]
	v_cndmask_b32_e64 v149, v149, v201, s[52:53]
	v_cndmask_b32_e64 v150, v150, v201, s[54:55]
	v_cndmask_b32_e64 v151, v151, v201, s[56:57]
	v_cndmask_b32_e64 v152, v152, v201, s[58:59]
	v_cndmask_b32_e64 v153, v153, v201, s[60:61]
	v_cndmask_b32_e64 v154, v154, v201, s[62:63]
	v_cndmask_b32_e64 v155, v155, v201, s[64:65]
	v_cndmask_b32_e64 v156, v156, v201, s[66:67]
	v_cndmask_b32_e64 v157, v157, v201, s[68:69]
	v_cndmask_b32_e64 v158, v158, v201, s[70:71]
	v_cndmask_b32_e64 v159, v159, v201, s[72:73]

.Lat_nomask8:
	v_exp_f32_e32 v160, v160
	v_exp_f32_e32 v161, v161
	v_add_f32_e32 v194, v194, v160
	v_exp_f32_e32 v162, v162
	s_waitcnt lgkmcnt(8)
	v_mfma_f32_16x16x32_bf16 v[0:3], v[80:83], v[176:179], v[0:3]
	v_mov_b32_e32 v199, v161
	v_exp_f32_e32 v163, v163
	v_add_f32_e32 v194, v194, v162
	v_mfma_f32_16x16x32_bf16 v[0:3], v[84:87], v[180:183], v[0:3]
	v_cvt_pk_bf16_f32 v184, v160, v161
	v_exp_f32_e32 v164, v164
	v_mfma_f32_16x16x32_bf16 v[4:7], v[88:91], v[176:179], v[4:7]
	v_add_f32_e32 v199, v199, v163
	v_exp_f32_e32 v165, v165
	v_mfma_f32_16x16x32_bf16 v[4:7], v[92:95], v[180:183], v[4:7]
	v_add_f32_e32 v194, v194, v164
	v_cvt_pk_bf16_f32 v185, v162, v163
	v_mfma_f32_16x16x32_bf16 v[8:11], v[96:99], v[176:179], v[8:11]
	v_exp_f32_e32 v166, v166
	v_add_f32_e32 v199, v199, v165
	v_exp_f32_e32 v167, v167
	v_mfma_f32_16x16x32_bf16 v[8:11], v[100:103], v[180:183], v[8:11]
	v_add_f32_e32 v194, v194, v166
	v_cvt_pk_bf16_f32 v186, v164, v165
	v_mfma_f32_16x16x32_bf16 v[12:15], v[104:107], v[176:179], v[12:15]
	v_exp_f32_e32 v168, v168
	v_add_f32_e32 v199, v199, v167
	v_mfma_f32_16x16x32_bf16 v[12:15], v[108:111], v[180:183], v[12:15]
	v_exp_f32_e32 v169, v169
	v_add_f32_e32 v194, v194, v168
	v_cvt_pk_bf16_f32 v187, v166, v167
	s_waitcnt lgkmcnt(6)
	v_mfma_f32_16x16x32_bf16 v[16:19], v[112:115], v[176:179], v[16:19]
	v_exp_f32_e32 v170, v170
	v_add_f32_e32 v199, v199, v169
	v_mfma_f32_16x16x32_bf16 v[16:19], v[116:119], v[180:183], v[16:19]
	v_exp_f32_e32 v171, v171
	v_add_f32_e32 v194, v194, v170
	s_waitcnt lgkmcnt(4)
	v_mfma_f32_16x16x32_bf16 v[20:23], v[120:123], v[176:179], v[20:23]
	v_cvt_pk_bf16_f32 v188, v168, v169
	v_exp_f32_e32 v172, v172
	v_add_f32_e32 v199, v199, v171
	v_mfma_f32_16x16x32_bf16 v[20:23], v[124:127], v[180:183], v[20:23]
	v_exp_f32_e32 v173, v173
	v_add_f32_e32 v194, v194, v172
	s_waitcnt lgkmcnt(2)
	v_mfma_f32_16x16x32_bf16 v[24:27], v[128:131], v[176:179], v[24:27]
	v_cvt_pk_bf16_f32 v189, v170, v171
	v_exp_f32_e32 v174, v174
	v_mfma_f32_16x16x32_bf16 v[24:27], v[132:135], v[180:183], v[24:27]
	v_add_f32_e32 v199, v199, v173
	v_exp_f32_e32 v175, v175
	s_waitcnt lgkmcnt(0)
	v_mfma_f32_16x16x32_bf16 v[28:31], v[136:139], v[176:179], v[28:31]
	v_add_f32_e32 v194, v194, v174
	v_cvt_pk_bf16_f32 v190, v172, v173
	v_add_f32_e32 v199, v199, v175
	v_mfma_f32_16x16x32_bf16 v[28:31], v[140:143], v[180:183], v[28:31]
	v_add_f32_e32 v194, v194, v199
	v_cvt_pk_bf16_f32 v191, v174, v175
	s_nop 1
	v_mfma_f32_16x16x32_bf16 v[32:35], v[80:83], v[184:187], v[32:35]
	v_mfma_f32_16x16x32_bf16 v[32:35], v[84:87], v[188:191], v[32:35]
	v_mfma_f32_16x16x32_bf16 v[36:39], v[88:91], v[184:187], v[36:39]
	v_mfma_f32_16x16x32_bf16 v[36:39], v[92:95], v[188:191], v[36:39]
	v_mfma_f32_16x16x32_bf16 v[40:43], v[96:99], v[184:187], v[40:43]
	v_mfma_f32_16x16x32_bf16 v[40:43], v[100:103], v[188:191], v[40:43]
	v_mfma_f32_16x16x32_bf16 v[44:47], v[104:107], v[184:187], v[44:47]
	v_mfma_f32_16x16x32_bf16 v[44:47], v[108:111], v[188:191], v[44:47]
	v_mfma_f32_16x16x32_bf16 v[48:51], v[112:115], v[184:187], v[48:51]
	v_mfma_f32_16x16x32_bf16 v[48:51], v[116:119], v[188:191], v[48:51]
	v_mfma_f32_16x16x32_bf16 v[52:55], v[120:123], v[184:187], v[52:55]
	v_mfma_f32_16x16x32_bf16 v[52:55], v[124:127], v[188:191], v[52:55]
	v_mfma_f32_16x16x32_bf16 v[56:59], v[128:131], v[184:187], v[56:59]
	v_mfma_f32_16x16x32_bf16 v[56:59], v[132:135], v[188:191], v[56:59]
	v_mfma_f32_16x16x32_bf16 v[60:63], v[136:139], v[184:187], v[60:63]
	v_mfma_f32_16x16x32_bf16 v[60:63], v[140:143], v[188:191], v[60:63]

.Lattn_tileB:
	s_add_i32 s0, s39, 3
	s_cmp_lt_i32 s0, s38
	s_cbranch_scc0 .Lat_nodmaB16
	s_add_i32 s1, s91, 3
	s_and_b32 s1, s1, 3
	s_lshl_b32 s1, s1, 15
	s_add_i32 s1, s1, s40
	s_add_i32 m0, s1, 0x0
	v_add_u32_e32 v210, s79, v197
	global_load_lds_dwordx4 v210, s[86:87]
	s_add_i32 m0, s1, 0x400
	v_add_u32_e32 v211, s79, v198
	global_load_lds_dwordx4 v211, s[86:87]
	s_add_i32 m0, s1, 0x800
	v_add_u32_e32 v212, s79, v229
	global_load_lds_dwordx4 v212, s[86:87]
	s_add_i32 m0, s1, 0xc00
	v_add_u32_e32 v213, s79, v230
	global_load_lds_dwordx4 v213, s[86:87]
	s_add_i32 s79, s79, s41

.Lat_s2end17:
	v_add_u32_e32 v195, 0x8000, v195
	v_add_u32_e32 v196, 0x8000, v196
	v_add_u32_e32 v231, 0x8000, v231
	v_add_u32_e32 v232, 0x8000, v232
	v_add_u32_e32 v233, 0x8000, v233
	v_add_u32_e32 v234, 0x8000, v234
	v_and_b32_e32 v195, 0x1ffff, v195
	v_and_b32_e32 v196, 0x1ffff, v196
	v_and_b32_e32 v231, 0x1ffff, v231
	v_and_b32_e32 v232, 0x1ffff, v232
	v_and_b32_e32 v233, 0x1ffff, v233
	v_and_b32_e32 v234, 0x1ffff, v234
	s_add_i32 s91, s91, 1
	s_add_i32 s39, s39, 1
	s_cmp_lt_i32 s39, s38
	s_cbranch_scc0 .Lattn_loopdone
	s_lshl_b32 s96, s39, 6
	s_add_i32 s0, s37, 15
	s_cmp_gt_i32 s96, s0
	s_cselect_b32 vcc_hi, 1, 0
	s_cbranch_scc1 .Lat_s1end19
	ds_read_b128 v[80:83], v195
	ds_read_b128 v[84:87], v196
	ds_read_b128 v[88:91], v195 offset:4096
	ds_read_b128 v[92:95], v196 offset:4096
	ds_read_b128 v[96:99], v195 offset:8192
	ds_read_b128 v[100:103], v196 offset:8192
	ds_read_b128 v[104:107], v195 offset:12288
	ds_read_b128 v[108:111], v196 offset:12288
	s_waitcnt lgkmcnt(6)
	v_mfma_f32_16x16x32_bf16 v[144:147], v[80:83], v[64:67], v[248:251]
	ds_read_b128 v[112:115], v231
	v_mfma_f32_16x16x32_bf16 v[144:147], v[84:87], v[68:71], v[144:147]
	ds_read_b128 v[116:119], v232
	s_waitcnt lgkmcnt(6)
	v_mfma_f32_16x16x32_bf16 v[148:151], v[88:91], v[64:67], v[248:251]
	ds_read_b128 v[120:123], v231 offset:4096
	v_mfma_f32_16x16x32_bf16 v[148:151], v[92:95], v[68:71], v[148:151]
	ds_read_b128 v[124:127], v232 offset:4096
	s_waitcnt lgkmcnt(6)
	v_mfma_f32_16x16x32_bf16 v[152:155], v[96:99], v[64:67], v[248:251]
	ds_read_b128 v[128:131], v231 offset:8192
	v_mfma_f32_16x16x32_bf16 v[152:155], v[100:103], v[68:71], v[152:155]
	ds_read_b128 v[132:135], v232 offset:8192
	s_waitcnt lgkmcnt(6)
	v_mfma_f32_16x16x32_bf16 v[156:159], v[104:107], v[64:67], v[248:251]
	ds_read_b128 v[136:139], v231 offset:12288
	v_mfma_f32_16x16x32_bf16 v[156:159], v[108:111], v[68:71], v[156:159]
	ds_read_b128 v[140:143], v232 offset:12288
	s_waitcnt lgkmcnt(0)
	v_mfma_f32_16x16x32_bf16 v[160:163], v[112:115], v[72:75], v[248:251]
	v_mfma_f32_16x16x32_bf16 v[160:163], v[116:119], v[76:79], v[160:163]
	s_add_i32 s0, s96, 63
	s_cmp_gt_i32 s0, s37
	s_cselect_b32 s97, 1, 0
	s_cbranch_scc0 .Lat_nomask20
	v_subrev_u32_e32 v207, s96, v200
	v_cmp_gt_i32_e64 s[42:43], 0, v207
	v_cmp_gt_i32_e64 s[44:45], 1, v207
	v_cmp_gt_i32_e64 s[46:47], 2, v207
	v_cmp_gt_i32_e64 s[48:49], 3, v207
	v_cmp_gt_i32_e64 s[50:51], 4, v207
	v_cmp_gt_i32_e64 s[52:53], 5, v207
	v_cmp_gt_i32_e64 s[54:55], 6, v207
	v_cmp_gt_i32_e64 s[56:57], 7, v207
	v_cmp_gt_i32_e64 s[58:59], 32, v207
	v_cmp_gt_i32_e64 s[60:61], 33, v207
	v_cmp_gt_i32_e64 s[62:63], 34, v207
	v_cmp_gt_i32_e64 s[64:65], 35, v207
	v_cmp_gt_i32_e64 s[66:67], 36, v207
	v_cmp_gt_i32_e64 s[68:69], 37, v207
	v_cmp_gt_i32_e64 s[70:71], 38, v207
	v_cmp_gt_i32_e64 s[72:73], 39, v207
	v_cndmask_b32_e64 v144, v144, v201, s[42:43]
	v_cndmask_b32_e64 v145, v145, v201, s[44:45]
	v_cndmask_b32_e64 v146, v146, v201, s[46:47]
	v_cndmask_b32_e64 v147, v147, v201, s[48:49]
	v_cndmask_b32_e64 v148, v148, v201, s[50:51]
	v_cndmask_b32_e64 v149, v149, v201, s[52:53]
	v_cndmask_b32_e64 v150, v150, v201, s[54:55]
	v_cndmask_b32_e64 v151, v151, v201, s[56:57]
	v_cndmask_b32_e64 v152, v152, v201, s[58:59]
	v_cndmask_b32_e64 v153, v153, v201, s[60:61]
	v_cndmask_b32_e64 v154, v154, v201, s[62:63]
	v_cndmask_b32_e64 v155, v155, v201, s[64:65]
	v_cndmask_b32_e64 v156, v156, v201, s[66:67]
	v_cndmask_b32_e64 v157, v157, v201, s[68:69]
	v_cndmask_b32_e64 v158, v158, v201, s[70:71]
	v_cndmask_b32_e64 v159, v159, v201, s[72:73]

.Lat_ubD25:
	s_lshl_b32 s38, s36, 1
	s_add_i32 s38, s38, 2
	s_add_i32 s1, s91, 0
	s_and_b32 s1, s1, 3
	s_lshl_b32 s1, s1, 15
	s_add_i32 s1, s1, s40
	s_add_i32 m0, s1, 0x0
	v_add_u32_e32 v210, s79, v197
	global_load_lds_dwordx4 v210, s[86:87]
	s_add_i32 m0, s1, 0x400
	v_add_u32_e32 v211, s79, v198
	global_load_lds_dwordx4 v211, s[86:87]
	s_add_i32 m0, s1, 0x800
	v_add_u32_e32 v212, s79, v229
	global_load_lds_dwordx4 v212, s[86:87]
	s_add_i32 m0, s1, 0xc00
	v_add_u32_e32 v213, s79, v230
	global_load_lds_dwordx4 v213, s[86:87]
	s_add_i32 s79, s79, s41
	s_add_i32 s1, s91, 1
	s_and_b32 s1, s1, 3
	s_lshl_b32 s1, s1, 15
	s_add_i32 s1, s1, s40
	s_add_i32 m0, s1, 0x0
	v_add_u32_e32 v210, s79, v197
	global_load_lds_dwordx4 v210, s[86:87]
	s_add_i32 m0, s1, 0x400
	v_add_u32_e32 v211, s79, v198
	global_load_lds_dwordx4 v211, s[86:87]
	s_add_i32 m0, s1, 0x800
	v_add_u32_e32 v212, s79, v229
	global_load_lds_dwordx4 v212, s[86:87]
	s_add_i32 m0, s1, 0xc00
	v_add_u32_e32 v213, s79, v230
	global_load_lds_dwordx4 v213, s[86:87]
	s_add_i32 s79, s79, s41
